# stack2 + lagging waves prefetch all V fragments of the deferred PV up front
# baseline (speedup 1.0000x reference)
.Lattn_lag:
	v_lshl_add_u32 v0, s52, 14, v234
	ds_read_b128 v[130:133], v0 offset:49152
	ds_read_b128 v[134:137], v0 offset:50176
	ds_read_b128 v[138:141], v0 offset:51200
	ds_read_b128 v[142:145], v0 offset:52224
	ds_read_b128 v[190:193], v0 offset:53248
	ds_read_b128 v[194:197], v0 offset:54272
	ds_read_b128 v[198:201], v0 offset:55296
	ds_read_b128 v[202:205], v0 offset:56320
	ds_read_b128 v[206:209], v0 offset:57344
	ds_read_b128 v[220:223], v0 offset:58368
	ds_read_b128 v[240:243], v0 offset:59392
	ds_read_b128 v[244:247], v0 offset:60416
	s_waitcnt lgkmcnt(10)
	v_mfma_f32_16x16x32_bf16 v[110:113], v[130:133], v[114:117], v[110:113]
	v_mfma_f32_16x16x32_bf16 v[30:33], v[130:133], v[122:125], v[30:33]
	v_mfma_f32_16x16x32_bf16 v[110:113], v[134:137], v[118:121], v[110:113]
	v_mfma_f32_16x16x32_bf16 v[30:33], v[134:137], v[126:129], v[30:33]
	ds_read_b128 v[130:133], v0 offset:61440
	ds_read_b128 v[134:137], v0 offset:62464
	s_waitcnt lgkmcnt(10)
	v_mfma_f32_16x16x32_bf16 v[106:109], v[138:141], v[114:117], v[106:109]
	v_mfma_f32_16x16x32_bf16 v[26:29], v[138:141], v[122:125], v[26:29]
	v_mfma_f32_16x16x32_bf16 v[106:109], v[142:145], v[118:121], v[106:109]
	v_mfma_f32_16x16x32_bf16 v[26:29], v[142:145], v[126:129], v[26:29]
	ds_read_b128 v[138:141], v0 offset:63488
	ds_read_b128 v[142:145], v0 offset:64512
	s_waitcnt lgkmcnt(10)
	v_mfma_f32_16x16x32_bf16 v[102:105], v[190:193], v[114:117], v[102:105]
	v_mfma_f32_16x16x32_bf16 v[22:25], v[190:193], v[122:125], v[22:25]
	v_mfma_f32_16x16x32_bf16 v[102:105], v[194:197], v[118:121], v[102:105]
	v_mfma_f32_16x16x32_bf16 v[22:25], v[194:197], v[126:129], v[22:25]
	s_waitcnt lgkmcnt(8)
	v_mfma_f32_16x16x32_bf16 v[98:101], v[198:201], v[114:117], v[98:101]
	v_mfma_f32_16x16x32_bf16 v[18:21], v[198:201], v[122:125], v[18:21]
	v_mfma_f32_16x16x32_bf16 v[98:101], v[202:205], v[118:121], v[98:101]
	v_mfma_f32_16x16x32_bf16 v[18:21], v[202:205], v[126:129], v[18:21]
	s_waitcnt lgkmcnt(6)
	v_mfma_f32_16x16x32_bf16 v[90:93], v[206:209], v[114:117], v[90:93]
	v_mfma_f32_16x16x32_bf16 v[14:17], v[206:209], v[122:125], v[14:17]
	v_mfma_f32_16x16x32_bf16 v[90:93], v[220:223], v[118:121], v[90:93]
	v_mfma_f32_16x16x32_bf16 v[14:17], v[220:223], v[126:129], v[14:17]
	s_waitcnt lgkmcnt(4)
	v_mfma_f32_16x16x32_bf16 v[70:73], v[240:243], v[114:117], v[70:73]
	v_mfma_f32_16x16x32_bf16 v[10:13], v[240:243], v[122:125], v[10:13]
	v_mfma_f32_16x16x32_bf16 v[70:73], v[244:247], v[118:121], v[70:73]
	v_mfma_f32_16x16x32_bf16 v[10:13], v[244:247], v[126:129], v[10:13]
	s_waitcnt lgkmcnt(2)
	v_mfma_f32_16x16x32_bf16 v[38:41], v[130:133], v[114:117], v[38:41]
	v_mfma_f32_16x16x32_bf16 v[6:9], v[130:133], v[122:125], v[6:9]
	v_mfma_f32_16x16x32_bf16 v[38:41], v[134:137], v[118:121], v[38:41]
	v_mfma_f32_16x16x32_bf16 v[6:9], v[134:137], v[126:129], v[6:9]
	s_waitcnt lgkmcnt(0)
	v_mfma_f32_16x16x32_bf16 v[34:37], v[138:141], v[114:117], v[34:37]
	v_mfma_f32_16x16x32_bf16 v[2:5], v[138:141], v[122:125], v[2:5]
	v_mfma_f32_16x16x32_bf16 v[34:37], v[142:145], v[118:121], v[34:37]
	v_mfma_f32_16x16x32_bf16 v[2:5], v[142:145], v[126:129], v[2:5]
	s_cmp_ge_u32 s53, s43
	s_cbranch_scc1 .Lattn_lag_nodma
	s_bitcmp1_b32 s53, 0
	s_cselect_b32 s54, 0x6000, 0
	s_add_i32 s54, s54, 0
	v_lshl_add_u64 v[130:131], v[180:181], 0, v[166:167]
	s_add_i32 m0, s54, s23
	s_nop 0
	global_load_lds_dwordx4 v[130:131], off
	v_lshl_add_u64 v[130:131], v[178:179], 0, v[166:167]
	s_add_i32 m0, s54, s24
	s_nop 0
	global_load_lds_dwordx4 v[130:131], off
	s_add_i32 m0, s54, s25
	s_lshl_b32 s54, s44, 14
	s_add_i32 s54, s54, 0
	v_lshl_add_u64 v[130:131], v[176:177], 0, v[166:167]
	s_add_i32 s56, s54, s23
	global_load_lds_dwordx4 v[130:131], off
	v_lshl_add_u64 v[130:131], v[182:183], 0, v[166:167]
	s_add_i32 m0, s56, 0xc000
	s_add_i32 s54, s54, s24
	global_load_lds_dwordx4 v[130:131], off
	v_lshl_add_u64 v[130:131], v[184:185], 0, v[166:167]
	s_add_i32 m0, s54, 0xc000
	s_nop 0
	global_load_lds_dwordx4 v[130:131], off
